# P8 epilogue: all 16 Y1B residual loads prefetched behind the slot store (counted vmcnt), 14 in-loop vmcnt(0) drains removed
# baseline (speedup 1.0000x reference)
.LBB0_986:
	s_or_b64 exec, exec, s[4:5]
	s_mov_b32 s98, s42
	s_ashr_i32 s99, s42, 31
	s_lshl_b64 s[98:99], s[98:99], 20
	s_add_u32 s98, s56, s98
	s_addc_u32 s99, s57, s99
	s_lshl_b32 s100, s40, 8
	s_or_b32 s100, s100, s61
	v_lshl_add_u32 v128, v139, 3, s100
	v_add_u32_e32 v254, s60, v138
	v_lshlrev_b32_e32 v128, 1, v128
	v_lshl_add_u32 v128, v254, 12, v128
	global_load_dwordx4 v[198:201], v128, s[98:99]
	global_load_dwordx4 v[230:233], v128, s[98:99] offset:256
	s_add_u32 s98, s98, 0x10000
	s_addc_u32 s99, s99, 0
	global_load_dwordx4 v[202:205], v128, s[98:99]
	global_load_dwordx4 v[234:237], v128, s[98:99] offset:256
	s_add_u32 s98, s98, 0x10000
	s_addc_u32 s99, s99, 0
	global_load_dwordx4 v[206:209], v128, s[98:99]
	global_load_dwordx4 v[238:241], v128, s[98:99] offset:256
	s_add_u32 s98, s98, 0x10000
	s_addc_u32 s99, s99, 0
	global_load_dwordx4 v[210:213], v128, s[98:99]
	global_load_dwordx4 v[242:245], v128, s[98:99] offset:256
	s_add_u32 s98, s98, 0x50000
	s_addc_u32 s99, s99, 0
	global_load_dwordx4 v[214:217], v128, s[98:99]
	global_load_dwordx4 v[246:249], v128, s[98:99] offset:256
	s_add_u32 s98, s98, 0x10000
	s_addc_u32 s99, s99, 0
	global_load_dwordx4 v[218:221], v128, s[98:99]
	global_load_dwordx4 v[250:253], v128, s[98:99] offset:256
	s_add_u32 s98, s98, 0x10000
	s_addc_u32 s99, s99, 0
	global_load_dwordx4 v[222:225], v128, s[98:99]
	global_load_dwordx4 v[130:133], v128, s[98:99] offset:256
	s_add_u32 s98, s98, 0x10000
	s_addc_u32 s99, s99, 0
	global_load_dwordx4 v[226:229], v128, s[98:99]
	global_load_dwordx4 v[154:157], v128, s[98:99] offset:256
	s_waitcnt vmcnt(16)
	v_cmp_eq_u32_e64 s[4:5], 0, v141
	s_and_saveexec_b64 s[46:47], s[4:5]
	s_cbranch_execz .LBB0_989
	s_mov_b64 s[48:49], exec
	v_mbcnt_lo_u32_b32 v137, s48, 0
	v_mbcnt_hi_u32_b32 v137, s49, v137
	v_cmp_eq_u32_e32 vcc, 0, v137
	s_and_b64 s[50:51], exec, vcc
	s_mov_b64 exec, s[50:51]
	s_cbranch_execz .LBB0_989
	s_lshl_b32 s50, s42, 6
	s_ashr_i32 s51, s50, 31
	s_lshl_b64 s[50:51], s[50:51], 2
	s_add_u32 s50, s25, s50
	s_addc_u32 s51, s33, s51
	s_bcnt1_i32_b64 s41, s[48:49]
	v_mov_b32_e32 v137, s41
	global_atomic_add v129, v137, s[50:51]

.LBB0_1006:
	s_or_b64 exec, exec, s[4:5]
	s_ashr_i32 s43, s42, 31
	s_lshl_b64 s[4:5], s[42:43], 20
	s_add_u32 s6, s56, s4
	s_addc_u32 s7, s57, s5
	s_lshl_b64 s[4:5], s[42:43], 21
	s_add_u32 s4, s94, s4
	s_addc_u32 s5, s95, s5
	s_lshl_b32 s40, s40, 8
	s_or_b32 s40, s40, s61
	v_lshl_add_u32 v140, v139, 3, s40
	s_lshl_b64 s[40:41], s[44:45], 2
	s_add_u32 s40, s86, s40
	v_ashrrev_i32_e32 v141, 31, v140
	s_addc_u32 s41, s87, s41
	v_add_u32_e32 v142, s60, v138
	v_lshlrev_b64 v[150:151], 2, v[140:141]
	v_lshl_add_u64 v[144:145], v[140:141], 1, s[6:7]
	v_ashrrev_i32_e32 v143, 31, v142
	v_lshl_add_u64 v[140:141], s[40:41], 0, v[150:151]
	v_lshlrev_b64 v[138:139], 12, v[142:143]
	v_add_co_u32_e32 v170, vcc, s24, v140
	s_waitcnt lgkmcnt(0)
	s_barrier
	v_lshl_add_u64 v[138:139], v[144:145], 0, v[138:139]
	v_addc_co_u32_e32 v171, vcc, 0, v141, vcc
	v_lshl_add_u64 v[136:137], s[14:15], 0, v[150:151]
	s_nop 0
	global_load_dwordx4 v[162:165], v[136:137], off offset:16
	global_load_dwordx4 v[166:169], v[136:137], off
	v_lshl_add_u64 v[140:141], v[140:141], 0, s[16:17]
	global_load_dwordx4 v[170:173], v[170:171], off
	v_lshl_add_u32 v161, v142, 2, 0
	global_load_dwordx4 v[174:177], v[140:141], off offset:16
	v_add_u32_e32 v161, 0x21200, v161
	ds_read2_b32 v[178:179], v161 offset1:16
	v_add_u32_e32 v180, 16, v142
	v_ashrrev_i32_e32 v181, 31, v180
	v_lshlrev_b64 v[182:183], 13, v[142:143]
	v_lshlrev_b64 v[184:185], 12, v[180:181]
	v_lshl_add_u64 v[150:151], s[4:5], 0, v[150:151]
	s_waitcnt lgkmcnt(0)
	v_pk_mul_f32 v[186:187], v[126:127], v[178:179] op_sel_hi:[1,0]
	v_pk_mul_f32 v[188:189], v[124:125], v[178:179] op_sel_hi:[1,0]
	v_pk_mul_f32 v[190:191], v[122:123], v[178:179] op_sel_hi:[1,0]
	v_pk_mul_f32 v[192:193], v[120:121], v[178:179] op_sel_hi:[1,0]
	v_lshl_add_u64 v[120:121], v[144:145], 0, v[184:185]
	v_lshl_add_u64 v[122:123], v[150:151], 0, v[182:183]
	s_andn2_b64 vcc, exec, s[0:1]
	s_mov_b64 s[0:1], -1
	s_waitcnt vmcnt(0)
	v_lshlrev_b32_e32 v182, 16, v198
	v_and_b32_e32 v183, 0xffff0000, v198
	v_lshlrev_b32_e32 v184, 16, v199
	v_and_b32_e32 v185, 0xffff0000, v199
	v_lshlrev_b32_e32 v194, 16, v200
	v_and_b32_e32 v195, 0xffff0000, v200
	v_lshlrev_b32_e32 v196, 16, v201
	v_and_b32_e32 v197, 0xffff0000, v201
	v_pk_mul_f32 v[146:147], v[168:169], v[172:173]
	v_pk_mul_f32 v[148:149], v[166:167], v[170:171]
	v_pk_mul_f32 v[126:127], v[164:165], v[176:177]
	v_pk_mul_f32 v[124:125], v[162:163], v[174:175]
	v_pk_fma_f32 v[164:165], v[146:147], v[186:187], v[184:185]
	v_pk_fma_f32 v[162:163], v[148:149], v[188:189], v[182:183]
	v_pk_fma_f32 v[168:169], v[126:127], v[190:191], v[196:197]
	v_pk_fma_f32 v[166:167], v[124:125], v[192:193], v[194:195]
	global_store_dwordx4 v[122:123], v[162:165], off nt
	global_store_dwordx4 v[122:123], v[166:169], off offset:16 nt
	s_nop 0
	v_mov_b32_e32 v172, v179
	v_add_u32_e32 v166, 32, v142
	v_ashrrev_i32_e32 v167, 31, v166
	v_lshlrev_b64 v[168:169], 13, v[180:181]
	v_lshlrev_b64 v[170:171], 12, v[166:167]
	v_pk_mul_f32 v[118:119], v[118:119], v[172:173] op_sel_hi:[1,0]
	v_pk_mul_f32 v[116:117], v[116:117], v[172:173] op_sel_hi:[1,0]
	v_pk_mul_f32 v[174:175], v[114:115], v[172:173] op_sel_hi:[1,0]
	v_lshl_add_u64 v[114:115], v[150:151], 0, v[168:169]
	v_pk_mul_f32 v[172:173], v[112:113], v[172:173] op_sel_hi:[1,0]
	v_lshl_add_u64 v[112:113], v[144:145], 0, v[170:171]
	v_lshlrev_b32_e32 v168, 16, v202
	v_and_b32_e32 v169, 0xffff0000, v202
	v_lshlrev_b32_e32 v162, 16, v203
	v_and_b32_e32 v163, 0xffff0000, v203
	v_lshlrev_b32_e32 v170, 16, v204
	v_and_b32_e32 v171, 0xffff0000, v204
	v_lshlrev_b32_e32 v164, 16, v205
	v_and_b32_e32 v165, 0xffff0000, v205
	v_pk_fma_f32 v[118:119], v[146:147], v[118:119], v[162:163]
	v_pk_fma_f32 v[116:117], v[148:149], v[116:117], v[168:169]
	v_pk_fma_f32 v[164:165], v[126:127], v[174:175], v[164:165]
	v_pk_fma_f32 v[162:163], v[124:125], v[172:173], v[170:171]
	global_store_dwordx4 v[114:115], v[116:119], off nt
	global_store_dwordx4 v[114:115], v[162:165], off offset:16 nt
	s_nop 0
	ds_read2_b32 v[170:171], v161 offset0:32 offset1:48
	v_add_u32_e32 v168, 48, v142
	v_ashrrev_i32_e32 v169, 31, v168
	v_lshlrev_b64 v[118:119], 13, v[166:167]
	v_lshlrev_b64 v[116:117], 12, v[168:169]
	s_waitcnt lgkmcnt(0)
	v_pk_mul_f32 v[110:111], v[110:111], v[170:171] op_sel_hi:[1,0]
	v_pk_mul_f32 v[108:109], v[108:109], v[170:171] op_sel_hi:[1,0]
	v_pk_mul_f32 v[166:167], v[106:107], v[170:171] op_sel_hi:[1,0]
	v_pk_mul_f32 v[172:173], v[104:105], v[170:171] op_sel_hi:[1,0]
	v_lshl_add_u64 v[118:119], v[150:151], 0, v[118:119]
	v_lshl_add_u64 v[116:117], v[144:145], 0, v[116:117]
	v_lshlrev_b32_e32 v104, 16, v206
	v_and_b32_e32 v105, 0xffff0000, v206
	v_lshlrev_b32_e32 v106, 16, v207
	v_and_b32_e32 v107, 0xffff0000, v207
	v_lshlrev_b32_e32 v162, 16, v208
	v_and_b32_e32 v163, 0xffff0000, v208
	v_lshlrev_b32_e32 v164, 16, v209
	v_and_b32_e32 v165, 0xffff0000, v209
	v_pk_fma_f32 v[106:107], v[146:147], v[110:111], v[106:107]
	v_pk_fma_f32 v[104:105], v[148:149], v[108:109], v[104:105]
	v_pk_fma_f32 v[110:111], v[126:127], v[166:167], v[164:165]
	v_pk_fma_f32 v[108:109], v[124:125], v[172:173], v[162:163]
	global_store_dwordx4 v[118:119], v[104:107], off nt
	global_store_dwordx4 v[118:119], v[108:111], off offset:16 nt
	s_nop 0
	v_mov_b32_e32 v164, v171
	v_add_u32_e32 v162, 0x80, v142
	v_lshlrev_b64 v[106:107], 13, v[168:169]
	v_pk_mul_f32 v[102:103], v[102:103], v[164:165] op_sel_hi:[1,0]
	v_pk_mul_f32 v[100:101], v[100:101], v[164:165] op_sel_hi:[1,0]
	v_pk_mul_f32 v[166:167], v[98:99], v[164:165] op_sel_hi:[1,0]
	v_pk_mul_f32 v[164:165], v[96:97], v[164:165] op_sel_hi:[1,0]
	v_ashrrev_i32_e32 v163, 31, v162
	v_lshl_add_u64 v[106:107], v[150:151], 0, v[106:107]
	v_lshlrev_b64 v[104:105], 12, v[162:163]
	v_lshl_add_u64 v[104:105], v[144:145], 0, v[104:105]
	v_lshlrev_b32_e32 v96, 16, v210
	v_and_b32_e32 v97, 0xffff0000, v210
	v_lshlrev_b32_e32 v98, 16, v211
	v_and_b32_e32 v99, 0xffff0000, v211
	v_lshlrev_b32_e32 v108, 16, v212
	v_and_b32_e32 v109, 0xffff0000, v212
	v_lshlrev_b32_e32 v110, 16, v213
	v_and_b32_e32 v111, 0xffff0000, v213
	v_pk_fma_f32 v[98:99], v[146:147], v[102:103], v[98:99]
	v_pk_fma_f32 v[96:97], v[148:149], v[100:101], v[96:97]
	v_pk_fma_f32 v[102:103], v[126:127], v[166:167], v[110:111]
	v_pk_fma_f32 v[100:101], v[124:125], v[164:165], v[108:109]
	global_store_dwordx4 v[106:107], v[96:99], off nt
	global_store_dwordx4 v[106:107], v[100:103], off offset:16 nt
	s_nop 0
	ds_read2_b32 v[110:111], v161 offset0:128 offset1:144
	v_add_u32_e32 v108, 0x90, v142
	v_ashrrev_i32_e32 v109, 31, v108
	v_lshlrev_b64 v[98:99], 13, v[162:163]
	v_lshlrev_b64 v[96:97], 12, v[108:109]
	s_waitcnt lgkmcnt(0)
	v_pk_mul_f32 v[94:95], v[94:95], v[110:111] op_sel_hi:[1,0]
	v_pk_mul_f32 v[92:93], v[92:93], v[110:111] op_sel_hi:[1,0]
	v_pk_mul_f32 v[162:163], v[90:91], v[110:111] op_sel_hi:[1,0]
	v_pk_mul_f32 v[164:165], v[88:89], v[110:111] op_sel_hi:[1,0]
	v_lshl_add_u64 v[98:99], v[150:151], 0, v[98:99]
	v_lshl_add_u64 v[96:97], v[144:145], 0, v[96:97]
	v_lshlrev_b32_e32 v88, 16, v214
	v_and_b32_e32 v89, 0xffff0000, v214
	v_lshlrev_b32_e32 v90, 16, v215
	v_and_b32_e32 v91, 0xffff0000, v215
	v_lshlrev_b32_e32 v100, 16, v216
	v_and_b32_e32 v101, 0xffff0000, v216
	v_lshlrev_b32_e32 v102, 16, v217
	v_and_b32_e32 v103, 0xffff0000, v217
	v_pk_fma_f32 v[90:91], v[146:147], v[94:95], v[90:91]
	v_pk_fma_f32 v[88:89], v[148:149], v[92:93], v[88:89]
	v_pk_fma_f32 v[94:95], v[126:127], v[162:163], v[102:103]
	v_pk_fma_f32 v[92:93], v[124:125], v[164:165], v[100:101]
	global_store_dwordx4 v[98:99], v[88:91], off nt
	global_store_dwordx4 v[98:99], v[92:95], off offset:16 nt
	s_nop 0
	v_mov_b32_e32 v102, v111
	v_add_u32_e32 v100, 0xa0, v142
	v_lshlrev_b64 v[90:91], 13, v[108:109]
	v_pk_mul_f32 v[86:87], v[86:87], v[102:103] op_sel_hi:[1,0]
	v_pk_mul_f32 v[84:85], v[84:85], v[102:103] op_sel_hi:[1,0]
	v_pk_mul_f32 v[108:109], v[82:83], v[102:103] op_sel_hi:[1,0]
	v_pk_mul_f32 v[102:103], v[80:81], v[102:103] op_sel_hi:[1,0]
	v_ashrrev_i32_e32 v101, 31, v100
	v_lshl_add_u64 v[90:91], v[150:151], 0, v[90:91]
	v_lshlrev_b64 v[88:89], 12, v[100:101]
	v_lshl_add_u64 v[88:89], v[144:145], 0, v[88:89]
	v_lshlrev_b32_e32 v80, 16, v218
	v_and_b32_e32 v81, 0xffff0000, v218
	v_lshlrev_b32_e32 v82, 16, v219
	v_and_b32_e32 v83, 0xffff0000, v219
	v_lshlrev_b32_e32 v92, 16, v220
	v_and_b32_e32 v93, 0xffff0000, v220
	v_lshlrev_b32_e32 v94, 16, v221
	v_and_b32_e32 v95, 0xffff0000, v221
	v_pk_fma_f32 v[82:83], v[146:147], v[86:87], v[82:83]
	v_pk_fma_f32 v[80:81], v[148:149], v[84:85], v[80:81]
	v_pk_fma_f32 v[86:87], v[126:127], v[108:109], v[94:95]
	v_pk_fma_f32 v[84:85], v[124:125], v[102:103], v[92:93]
	global_store_dwordx4 v[90:91], v[80:83], off nt
	global_store_dwordx4 v[90:91], v[84:87], off offset:16 nt
	s_nop 0
	ds_read2_b32 v[94:95], v161 offset0:160 offset1:176
	v_add_u32_e32 v92, 0xb0, v142
	v_ashrrev_i32_e32 v93, 31, v92
	v_lshlrev_b64 v[82:83], 13, v[100:101]
	v_lshlrev_b64 v[80:81], 12, v[92:93]
	s_waitcnt lgkmcnt(0)
	v_pk_mul_f32 v[78:79], v[78:79], v[94:95] op_sel_hi:[1,0]
	v_pk_mul_f32 v[76:77], v[76:77], v[94:95] op_sel_hi:[1,0]
	v_pk_mul_f32 v[100:101], v[74:75], v[94:95] op_sel_hi:[1,0]
	v_pk_mul_f32 v[102:103], v[72:73], v[94:95] op_sel_hi:[1,0]
	v_lshl_add_u64 v[82:83], v[150:151], 0, v[82:83]
	v_lshl_add_u64 v[80:81], v[144:145], 0, v[80:81]
	v_lshlrev_b32_e32 v72, 16, v222
	v_and_b32_e32 v73, 0xffff0000, v222
	v_lshlrev_b32_e32 v74, 16, v223
	v_and_b32_e32 v75, 0xffff0000, v223
	v_lshlrev_b32_e32 v84, 16, v224
	v_and_b32_e32 v85, 0xffff0000, v224
	v_lshlrev_b32_e32 v86, 16, v225
	v_and_b32_e32 v87, 0xffff0000, v225
	v_pk_fma_f32 v[74:75], v[146:147], v[78:79], v[74:75]
	v_pk_fma_f32 v[72:73], v[148:149], v[76:77], v[72:73]
	v_pk_fma_f32 v[78:79], v[126:127], v[100:101], v[86:87]
	v_pk_fma_f32 v[76:77], v[124:125], v[102:103], v[84:85]
	global_store_dwordx4 v[82:83], v[72:75], off nt
	global_store_dwordx4 v[82:83], v[76:79], off offset:16 nt
	s_nop 0
	v_lshlrev_b64 v[72:73], 13, v[92:93]
	v_mov_b32_e32 v78, v95
	v_pk_mul_f32 v[70:71], v[70:71], v[78:79] op_sel_hi:[1,0]
	v_pk_mul_f32 v[68:69], v[68:69], v[78:79] op_sel_hi:[1,0]
	v_pk_mul_f32 v[84:85], v[66:67], v[78:79] op_sel_hi:[1,0]
	v_pk_mul_f32 v[78:79], v[64:65], v[78:79] op_sel_hi:[1,0]
	v_lshl_add_u64 v[72:73], v[150:151], 0, v[72:73]
	v_lshlrev_b32_e32 v64, 16, v226
	v_and_b32_e32 v65, 0xffff0000, v226
	v_lshlrev_b32_e32 v66, 16, v227
	v_and_b32_e32 v67, 0xffff0000, v227
	v_lshlrev_b32_e32 v74, 16, v228
	v_and_b32_e32 v75, 0xffff0000, v228
	v_lshlrev_b32_e32 v76, 16, v229
	v_and_b32_e32 v77, 0xffff0000, v229
	v_pk_fma_f32 v[66:67], v[146:147], v[70:71], v[66:67]
	v_pk_fma_f32 v[64:65], v[148:149], v[68:69], v[64:65]
	v_pk_fma_f32 v[70:71], v[126:127], v[84:85], v[76:77]
	v_pk_fma_f32 v[68:69], v[124:125], v[78:79], v[74:75]
	global_store_dwordx4 v[72:73], v[64:67], off nt
	global_store_dwordx4 v[72:73], v[68:71], off offset:16 nt
	global_load_dwordx4 v[64:67], v[140:141], off offset:512
	global_load_dwordx4 v[68:71], v[136:137], off offset:512
	global_load_dwordx4 v[74:77], v[136:137], off offset:528
	global_load_dwordx4 v[84:87], v[140:141], off offset:528
	s_nop 0
	ds_read2_b32 v[78:79], v161 offset1:16
	s_waitcnt lgkmcnt(0)
	v_pk_mul_f32 v[100:101], v[62:63], v[78:79] op_sel_hi:[1,0]
	v_pk_mul_f32 v[102:103], v[60:61], v[78:79] op_sel_hi:[1,0]
	v_pk_mul_f32 v[108:109], v[58:59], v[78:79] op_sel_hi:[1,0]
	v_pk_mul_f32 v[110:111], v[56:57], v[78:79] op_sel_hi:[1,0]
	s_waitcnt vmcnt(2)
	v_pk_mul_f32 v[60:61], v[70:71], v[66:67]
	v_pk_mul_f32 v[62:63], v[68:69], v[64:65]
	s_waitcnt vmcnt(0)
	v_pk_mul_f32 v[58:59], v[76:77], v[86:87]
	v_lshlrev_b32_e32 v64, 16, v230
	v_and_b32_e32 v65, 0xffff0000, v230
	v_lshlrev_b32_e32 v66, 16, v231
	v_and_b32_e32 v67, 0xffff0000, v231
	v_pk_mul_f32 v[56:57], v[74:75], v[84:85]
	v_lshlrev_b32_e32 v68, 16, v232
	v_and_b32_e32 v69, 0xffff0000, v232
	v_lshlrev_b32_e32 v70, 16, v233
	v_and_b32_e32 v71, 0xffff0000, v233
	v_pk_fma_f32 v[66:67], v[60:61], v[100:101], v[66:67]
	v_pk_fma_f32 v[64:65], v[62:63], v[102:103], v[64:65]
	v_pk_fma_f32 v[70:71], v[58:59], v[108:109], v[70:71]
	v_pk_fma_f32 v[68:69], v[56:57], v[110:111], v[68:69]
	global_store_dwordx4 v[122:123], v[64:67], off offset:512 nt
	global_store_dwordx4 v[122:123], v[68:71], off offset:528 nt
	s_nop 0
	s_nop 0
	v_mov_b32_e32 v68, v79
	v_pk_mul_f32 v[54:55], v[54:55], v[68:69] op_sel_hi:[1,0]
	v_pk_mul_f32 v[52:53], v[52:53], v[68:69] op_sel_hi:[1,0]
	v_pk_mul_f32 v[70:71], v[50:51], v[68:69] op_sel_hi:[1,0]
	v_pk_mul_f32 v[68:69], v[48:49], v[68:69] op_sel_hi:[1,0]
	v_lshlrev_b32_e32 v48, 16, v234
	v_and_b32_e32 v49, 0xffff0000, v234
	v_lshlrev_b32_e32 v50, 16, v235
	v_and_b32_e32 v51, 0xffff0000, v235
	v_lshlrev_b32_e32 v64, 16, v236
	v_and_b32_e32 v65, 0xffff0000, v236
	v_lshlrev_b32_e32 v66, 16, v237
	v_and_b32_e32 v67, 0xffff0000, v237
	v_pk_fma_f32 v[50:51], v[60:61], v[54:55], v[50:51]
	v_pk_fma_f32 v[48:49], v[62:63], v[52:53], v[48:49]
	v_pk_fma_f32 v[54:55], v[58:59], v[70:71], v[66:67]
	v_pk_fma_f32 v[52:53], v[56:57], v[68:69], v[64:65]
	global_store_dwordx4 v[114:115], v[48:51], off offset:512 nt
	global_store_dwordx4 v[114:115], v[52:55], off offset:528 nt
	s_nop 0
	ds_read2_b32 v[52:53], v161 offset0:32 offset1:48
	s_waitcnt lgkmcnt(0)
	v_pk_mul_f32 v[46:47], v[46:47], v[52:53] op_sel_hi:[1,0]
	v_pk_mul_f32 v[44:45], v[44:45], v[52:53] op_sel_hi:[1,0]
	v_pk_mul_f32 v[54:55], v[42:43], v[52:53] op_sel_hi:[1,0]
	v_pk_mul_f32 v[64:65], v[40:41], v[52:53] op_sel_hi:[1,0]
	v_lshlrev_b32_e32 v40, 16, v238
	v_and_b32_e32 v41, 0xffff0000, v238
	v_lshlrev_b32_e32 v42, 16, v239
	v_and_b32_e32 v43, 0xffff0000, v239
	v_lshlrev_b32_e32 v48, 16, v240
	v_and_b32_e32 v49, 0xffff0000, v240
	v_lshlrev_b32_e32 v50, 16, v241
	v_and_b32_e32 v51, 0xffff0000, v241
	v_pk_fma_f32 v[42:43], v[60:61], v[46:47], v[42:43]
	v_pk_fma_f32 v[40:41], v[62:63], v[44:45], v[40:41]
	v_pk_fma_f32 v[46:47], v[58:59], v[54:55], v[50:51]
	v_pk_fma_f32 v[44:45], v[56:57], v[64:65], v[48:49]
	global_store_dwordx4 v[118:119], v[40:43], off offset:512 nt
	global_store_dwordx4 v[118:119], v[44:47], off offset:528 nt
	s_nop 0
	s_nop 0
	v_mov_b32_e32 v44, v53
	v_pk_mul_f32 v[38:39], v[38:39], v[44:45] op_sel_hi:[1,0]
	v_pk_mul_f32 v[36:37], v[36:37], v[44:45] op_sel_hi:[1,0]
	v_pk_mul_f32 v[46:47], v[34:35], v[44:45] op_sel_hi:[1,0]
	v_pk_mul_f32 v[44:45], v[32:33], v[44:45] op_sel_hi:[1,0]
	v_lshlrev_b32_e32 v32, 16, v242
	v_and_b32_e32 v33, 0xffff0000, v242
	v_lshlrev_b32_e32 v34, 16, v243
	v_and_b32_e32 v35, 0xffff0000, v243
	v_lshlrev_b32_e32 v40, 16, v244
	v_and_b32_e32 v41, 0xffff0000, v244
	v_lshlrev_b32_e32 v42, 16, v245
	v_and_b32_e32 v43, 0xffff0000, v245
	v_pk_fma_f32 v[34:35], v[60:61], v[38:39], v[34:35]
	v_pk_fma_f32 v[32:33], v[62:63], v[36:37], v[32:33]
	v_pk_fma_f32 v[38:39], v[58:59], v[46:47], v[42:43]
	v_pk_fma_f32 v[36:37], v[56:57], v[44:45], v[40:41]
	global_store_dwordx4 v[106:107], v[32:35], off offset:512 nt
	global_store_dwordx4 v[106:107], v[36:39], off offset:528 nt
	s_nop 0
	ds_read2_b32 v[36:37], v161 offset0:128 offset1:144
	s_waitcnt lgkmcnt(0)
	v_pk_mul_f32 v[30:31], v[30:31], v[36:37] op_sel_hi:[1,0]
	v_pk_mul_f32 v[28:29], v[28:29], v[36:37] op_sel_hi:[1,0]
	v_pk_mul_f32 v[38:39], v[26:27], v[36:37] op_sel_hi:[1,0]
	v_pk_mul_f32 v[40:41], v[24:25], v[36:37] op_sel_hi:[1,0]
	v_lshlrev_b32_e32 v24, 16, v246
	v_and_b32_e32 v25, 0xffff0000, v246
	v_lshlrev_b32_e32 v26, 16, v247
	v_and_b32_e32 v27, 0xffff0000, v247
	v_lshlrev_b32_e32 v32, 16, v248
	v_and_b32_e32 v33, 0xffff0000, v248
	v_lshlrev_b32_e32 v34, 16, v249
	v_and_b32_e32 v35, 0xffff0000, v249
	v_pk_fma_f32 v[26:27], v[60:61], v[30:31], v[26:27]
	v_pk_fma_f32 v[24:25], v[62:63], v[28:29], v[24:25]
	v_pk_fma_f32 v[30:31], v[58:59], v[38:39], v[34:35]
	v_pk_fma_f32 v[28:29], v[56:57], v[40:41], v[32:33]
	global_store_dwordx4 v[98:99], v[24:27], off offset:512 nt
	global_store_dwordx4 v[98:99], v[28:31], off offset:528 nt
	s_nop 0
	s_nop 0
	v_mov_b32_e32 v28, v37
	v_pk_mul_f32 v[22:23], v[22:23], v[28:29] op_sel_hi:[1,0]
	v_pk_mul_f32 v[20:21], v[20:21], v[28:29] op_sel_hi:[1,0]
	v_pk_mul_f32 v[30:31], v[18:19], v[28:29] op_sel_hi:[1,0]
	v_pk_mul_f32 v[28:29], v[16:17], v[28:29] op_sel_hi:[1,0]
	v_lshlrev_b32_e32 v16, 16, v250
	v_and_b32_e32 v17, 0xffff0000, v250
	v_lshlrev_b32_e32 v18, 16, v251
	v_and_b32_e32 v19, 0xffff0000, v251
	v_lshlrev_b32_e32 v24, 16, v252
	v_and_b32_e32 v25, 0xffff0000, v252
	v_lshlrev_b32_e32 v26, 16, v253
	v_and_b32_e32 v27, 0xffff0000, v253
	v_pk_fma_f32 v[18:19], v[60:61], v[22:23], v[18:19]
	v_pk_fma_f32 v[16:17], v[62:63], v[20:21], v[16:17]
	v_pk_fma_f32 v[22:23], v[58:59], v[30:31], v[26:27]
	v_pk_fma_f32 v[20:21], v[56:57], v[28:29], v[24:25]
	global_store_dwordx4 v[90:91], v[16:19], off offset:512 nt
	global_store_dwordx4 v[90:91], v[20:23], off offset:528 nt
	s_nop 0
	ds_read2_b32 v[20:21], v161 offset0:160 offset1:176
	s_waitcnt lgkmcnt(0)
	v_pk_mul_f32 v[14:15], v[14:15], v[20:21] op_sel_hi:[1,0]
	v_pk_mul_f32 v[12:13], v[12:13], v[20:21] op_sel_hi:[1,0]
	v_pk_mul_f32 v[22:23], v[10:11], v[20:21] op_sel_hi:[1,0]
	v_pk_mul_f32 v[24:25], v[8:9], v[20:21] op_sel_hi:[1,0]
	v_lshlrev_b32_e32 v8, 16, v130
	v_and_b32_e32 v9, 0xffff0000, v130
	v_lshlrev_b32_e32 v10, 16, v131
	v_and_b32_e32 v11, 0xffff0000, v131
	v_lshlrev_b32_e32 v16, 16, v132
	v_and_b32_e32 v17, 0xffff0000, v132
	v_lshlrev_b32_e32 v18, 16, v133
	v_and_b32_e32 v19, 0xffff0000, v133
	v_pk_fma_f32 v[10:11], v[60:61], v[14:15], v[10:11]
	v_pk_fma_f32 v[8:9], v[62:63], v[12:13], v[8:9]
	v_pk_fma_f32 v[14:15], v[58:59], v[22:23], v[18:19]
	v_pk_fma_f32 v[12:13], v[56:57], v[24:25], v[16:17]
	global_store_dwordx4 v[82:83], v[8:11], off offset:512 nt
	global_store_dwordx4 v[82:83], v[12:15], off offset:528 nt
	s_nop 0
	s_nop 0
	v_mov_b32_e32 v12, v21
	v_pk_mul_f32 v[6:7], v[6:7], v[12:13] op_sel_hi:[1,0]
	v_pk_mul_f32 v[4:5], v[4:5], v[12:13] op_sel_hi:[1,0]
	v_pk_mul_f32 v[14:15], v[2:3], v[12:13] op_sel_hi:[1,0]
	v_pk_mul_f32 v[12:13], v[0:1], v[12:13] op_sel_hi:[1,0]
	v_lshlrev_b32_e32 v0, 16, v154
	v_and_b32_e32 v1, 0xffff0000, v154
	v_lshlrev_b32_e32 v2, 16, v155
	v_and_b32_e32 v3, 0xffff0000, v155
	v_lshlrev_b32_e32 v8, 16, v156
	v_and_b32_e32 v9, 0xffff0000, v156
	v_lshlrev_b32_e32 v10, 16, v157
	v_and_b32_e32 v11, 0xffff0000, v157
	v_pk_fma_f32 v[2:3], v[60:61], v[6:7], v[2:3]
	v_pk_fma_f32 v[0:1], v[62:63], v[4:5], v[0:1]
	v_pk_fma_f32 v[6:7], v[58:59], v[14:15], v[10:11]
	v_pk_fma_f32 v[4:5], v[56:57], v[12:13], v[8:9]
	global_store_dwordx4 v[72:73], v[0:3], off offset:512 nt
	global_store_dwordx4 v[72:73], v[4:7], off offset:528 nt
	s_cbranch_vccnz .LBB0_955
	s_andn2_b64 vcc, exec, s[10:11]
	s_cbranch_vccnz .LBB0_954
	s_barrier
	s_branch .LBB0_954

	.amdhsa_kernel _Z10fwd_kernel4Args
		.amdhsa_group_segment_fixed_size 0
		.amdhsa_private_segment_fixed_size 0
		.amdhsa_kernarg_size 480
		.amdhsa_user_sgpr_count 2
		.amdhsa_user_sgpr_dispatch_ptr 0
		.amdhsa_user_sgpr_queue_ptr 0
		.amdhsa_user_sgpr_kernarg_segment_ptr 1
		.amdhsa_user_sgpr_dispatch_id 0
		.amdhsa_user_sgpr_kernarg_preload_length 0
		.amdhsa_user_sgpr_kernarg_preload_offset 0
		.amdhsa_user_sgpr_private_segment_size 0
		.amdhsa_uses_dynamic_stack 0
		.amdhsa_enable_private_segment 0
		.amdhsa_system_sgpr_workgroup_id_x 1
		.amdhsa_system_sgpr_workgroup_id_y 0
		.amdhsa_system_sgpr_workgroup_id_z 0
		.amdhsa_system_sgpr_workgroup_info 0
		.amdhsa_system_vgpr_workitem_id 0
		.amdhsa_next_free_vgpr 256
		.amdhsa_next_free_sgpr 102
		.amdhsa_accum_offset 256
		.amdhsa_reserve_vcc 1
		.amdhsa_float_round_mode_32 0
		.amdhsa_float_round_mode_16_64 0
		.amdhsa_float_denorm_mode_32 3
		.amdhsa_float_denorm_mode_16_64 3
		.amdhsa_dx10_clamp 1
		.amdhsa_ieee_mode 1
		.amdhsa_fp16_overflow 0
		.amdhsa_tg_split 0
		.amdhsa_exception_fp_ieee_invalid_op 0
		.amdhsa_exception_fp_denorm_src 0
		.amdhsa_exception_fp_ieee_div_zero 0
		.amdhsa_exception_fp_ieee_overflow 0
		.amdhsa_exception_fp_ieee_underflow 0
		.amdhsa_exception_fp_ieee_inexact 0
		.amdhsa_exception_int_div_zero 0
	.end_amdhsa_kernel

.Lfunc_end0:
	.size	_Z10fwd_kernel4Args, .Lfunc_end0-_Z10fwd_kernel4Args
	.set _Z10fwd_kernel4Args.num_vgpr, 256
	.set _Z10fwd_kernel4Args.num_agpr, 0
	.set _Z10fwd_kernel4Args.numbered_sgpr, 102
	.set _Z10fwd_kernel4Args.num_named_barrier, 0
	.set _Z10fwd_kernel4Args.private_seg_size, 0
	.set _Z10fwd_kernel4Args.uses_vcc, 1
	.set _Z10fwd_kernel4Args.uses_flat_scratch, 0
	.set _Z10fwd_kernel4Args.has_dyn_sized_stack, 0
	.set _Z10fwd_kernel4Args.has_recursion, 0
	.set _Z10fwd_kernel4Args.has_indirect_call, 0

amdhsa.kernels:
  - .agpr_count:     0
    .args:
      - .offset:         0
        .size:           224
        .value_kind:     by_value
      - .offset:         224
        .size:           4
        .value_kind:     hidden_block_count_x
      - .offset:         228
        .size:           4
        .value_kind:     hidden_block_count_y
      - .offset:         232
        .size:           4
        .value_kind:     hidden_block_count_z
      - .offset:         236
        .size:           2
        .value_kind:     hidden_group_size_x
      - .offset:         238
        .size:           2
        .value_kind:     hidden_group_size_y
      - .offset:         240
        .size:           2
        .value_kind:     hidden_group_size_z
      - .offset:         242
        .size:           2
        .value_kind:     hidden_remainder_x
      - .offset:         244
        .size:           2
        .value_kind:     hidden_remainder_y
      - .offset:         246
        .size:           2
        .value_kind:     hidden_remainder_z
      - .offset:         264
        .size:           8
        .value_kind:     hidden_global_offset_x
      - .offset:         272
        .size:           8
        .value_kind:     hidden_global_offset_y
      - .offset:         280
        .size:           8
        .value_kind:     hidden_global_offset_z
      - .offset:         288
        .size:           2
        .value_kind:     hidden_grid_dims
      - .offset:         344
        .size:           4
        .value_kind:     hidden_dynamic_lds_size
    .group_segment_fixed_size: 0
    .kernarg_segment_align: 8
    .kernarg_segment_size: 480
    .language:       OpenCL C
    .language_version:
      - 2
      - 0
    .max_flat_workgroup_size: 512
    .name:           _Z10fwd_kernel4Args
    .private_segment_fixed_size: 0
    .sgpr_count:     108
    .sgpr_spill_count: 51
    .symbol:         _Z10fwd_kernel4Args.kd
    .uniform_work_group_size: 1
    .uses_dynamic_stack: false
    .vgpr_count:     256
    .vgpr_spill_count: 0
    .wavefront_size: 64
